# retention scan: XOR swizzle of the 16-byte chunk index in the ST / VT LDS images (ds_read_b128 lane groups were 2-way bank conflicted)
# speedup vs baseline: 1.0079x; 1.0065x over previous
.LBB0_1313:
	s_or_b64 exec, exec, s[0:1]
	s_add_u32 s6, s94, 0x2a402800
	s_addc_u32 s7, s95, 0
	s_cmpk_gt_u32 s2, 0x7f
	s_waitcnt lgkmcnt(0)
	s_barrier
	s_cbranch_scc1 .LBB0_1326
	s_and_b32 s76, s2, 7
	s_lshr_b32 s77, s2, 3
	s_lshr_b32 s78, s77, 3
	s_lshl_b32 s72, s76, 1
	s_add_u32 s72, s72, s78
	s_and_b32 s73, s77, 7
	s_lshr_b32 s74, s72, 2
	s_and_b32 s75, s72, 3
	s_mov_b32 s82, 0xbd020aec
	s_cmp_eq_u32 s75, 1
	s_cselect_b32 s82, 0xbc8102b3, s82
	s_cmp_eq_u32 s75, 2
	s_cselect_b32 s82, 0xbc0080ac, s82
	s_cmp_eq_u32 s75, 3
	s_cselect_b32 s82, 0xbb80402b, s82
	v_lshrrev_b32_e32 v210, 6, v198
	v_and_b32_e32 v211, 15, v198
	v_bfe_u32 v212, v198, 4, 2
	v_readfirstlane_b32 s71, v210
	v_lshl_or_b32 v213, v210, 4, v211
	v_add_u32_e32 v213, 1, v213
	v_cvt_f32_i32_e32 v213, v213
	v_mul_f32_e32 v213, s82, v213
	v_mul_f32_e32 v213, 0x3fb8aa3b, v213
	v_exp_f32_e32 v202, v213
	v_mov_b32_e32 v213, 0x43000000
	v_mul_f32_e32 v213, s82, v213
	v_mul_f32_e32 v213, 0x3fb8aa3b, v213
	v_exp_f32_e32 v204, v213
	s_nop 1
	v_mov_b32_e32 v203, v202
	v_mov_b32_e32 v205, v204
	v_lshlrev_b32_e32 v192, 4, v211
	v_lshl_add_u32 v192, v212, 8, v192
	v_lshlrev_b32_e32 v193, 11, v211
	v_lshl_add_u32 v193, v212, 4, v193
	v_and_b32_e32 v213, 63, v198
	v_lshrrev_b32_e32 v195, 3, v213
	v_and_b32_e32 v215, 7, v213
	v_mul_u32_u24_e32 v214, 144, v195
	v_lshl_add_u32 v215, v215, 4, v214
	v_and_b32_e32 v214, 7, v213
	v_lshlrev_b32_e32 v195, 12, v195
	v_lshl_add_u32 v195, v214, 4, v195
	v_add_u32_e32 v220, 0x8000, v195
	v_mul_u32_u24_e32 v214, 144, v211
	v_lshl_add_u32 v214, v212, 3, v214
	v_mul_u32_u24_e32 v213, 2304, v210
	v_add_u32_e32 v213, 102400, v213
	v_add_u32_e32 v214, v214, v213
	v_add_u32_e32 v215, v215, v213
	v_lshrrev_b32_e32 v213, 3, v198
	v_and_b32_e32 v194, 7, v198
	v_lshlrev_b32_e32 v194, 4, v194
	v_lshrrev_b32_e32 v218, 2, v213
	v_lshrrev_b32_e32 v219, 3, v213
	v_xor_b32_e32 v218, v218, v219
	v_and_b32_e32 v218, 1, v218
	v_and_b32_e32 v219, 7, v198
	v_xor_b32_e32 v219, v219, v218
	v_mul_u32_u24_e32 v201, 272, v213
	v_lshl_add_u32 v201, v219, 4, v201
	v_lshrrev_b32_e32 v216, 2, v211
	v_lshrrev_b32_e32 v217, 3, v211
	v_xor_b32_e32 v216, v216, v217
	v_and_b32_e32 v216, 1, v216
	v_xor_b32_e32 v217, v212, v216
	v_lshlrev_b32_e32 v218, 3, v212
	v_lshlrev_b32_e32 v216, 4, v216
	v_xor_b32_e32 v218, v218, v216
	v_lshl_add_u32 v194, v213, 13, v194
	v_add_u32_e32 v201, 67584, v201
	v_mul_u32_u24_e32 v196, 528, v211
	v_add_u32_e32 v200, v218, v196
	v_lshl_add_u32 v200, v210, 6, v200
	v_add_u32_e32 v200, 33792, v200
	v_lshl_add_u32 v196, v217, 4, v196
	v_mul_u32_u24_e32 v197, 272, v211
	v_lshl_add_u32 v197, v217, 4, v197
	v_add_u32_e32 v197, 67584, v197
	v_lshlrev_b32_e32 v206, 13, v212
	v_lshl_add_u32 v206, v211, 2, v206
	v_add_u32_e32 v207, 2048, v206
	v_add_u32_e32 v208, 4096, v206
	v_add_u32_e32 v209, 6144, v206
	s_mov_b32 s76, 0x27402800
	s_lshl_b32 s77, s72, 20
	s_add_u32 s76, s76, s77
	s_lshl_b32 s77, s71, 12
	s_add_u32 s76, s76, s77
	s_add_u32 s62, s94, s76
	s_addc_u32 s63, s95, 0
	s_mov_b32 s76, 0x28403800
	s_lshl_b32 s77, s72, 21
	s_add_u32 s76, s76, s77
	s_lshl_b32 s77, s71, 13
	s_add_u32 s76, s76, s77
	s_add_u32 s64, s94, s76
	s_addc_u32 s65, s95, 0
	s_mov_b32 s76, 0x1a802800
	s_lshl_b32 s77, s74, 23
	s_add_u32 s76, s76, s77
	s_lshl_b32 s77, s71, 15
	s_add_u32 s76, s76, s77
	s_lshl_b32 s77, s75, 9
	s_add_u32 s76, s76, s77
	s_add_u32 s60, s94, s76
	s_addc_u32 s61, s95, 0
	s_mov_b32 s76, 0x23002800
	s_lshl_b32 s77, s72, 22
	s_add_u32 s76, s76, s77
	s_lshl_b32 s77, s73, 19
	s_add_u32 s76, s76, s77
	s_add_u32 s66, s94, s76
	s_addc_u32 s67, s95, 0
	s_mov_b32 s76, 0x2a402800
	s_lshl_b32 s77, s74, 24
	s_add_u32 s76, s76, s77
	s_lshl_b32 s77, s71, 16
	s_add_u32 s76, s76, s77
	s_lshl_b32 s77, s75, 10
	s_add_u32 s76, s76, s77
	s_lshl_b32 s77, s73, 7
	s_add_u32 s76, s76, s77
	s_add_u32 s68, s94, s76
	s_addc_u32 s69, s95, 0
	s_mov_b32 s76, 0x6500000
	s_lshl_b32 s77, s72, 19
	s_add_u32 s76, s76, s77
	s_lshl_b32 s77, s71, 16
	s_add_u32 s76, s76, s77
	s_lshl_b32 s77, s73, 8
	s_add_u32 s76, s76, s77
	s_add_u32 s44, s92, s76
	s_addc_u32 s45, s93, 0
	s_add_u32 s46, s44, 0x8000
	s_addc_u32 s47, s45, 0
	global_load_dwordx4 v[176:179], v194, s[66:67]
	global_load_dwordx4 v[180:183], v194, s[66:67] offset:128
	global_load_dwordx4 v[0:3], v193, s[60:61]
	global_load_dwordx4 v[4:7], v193, s[60:61] offset:64
	global_load_dwordx4 v[8:11], v193, s[60:61] offset:128
	global_load_dwordx4 v[12:15], v193, s[60:61] offset:192
	global_load_dwordx4 v[16:19], v193, s[60:61] offset:256
	global_load_dwordx4 v[20:23], v193, s[60:61] offset:320
	global_load_dwordx4 v[24:27], v193, s[60:61] offset:384
	global_load_dwordx4 v[28:31], v193, s[60:61] offset:448
	global_load_dwordx4 v[32:35], v192, s[62:63]
	global_load_dwordx4 v[36:39], v192, s[62:63] offset:1024
	global_load_dwordx4 v[40:43], v192, s[62:63] offset:2048
	global_load_dwordx4 v[44:47], v192, s[62:63] offset:3072
	global_load_dwordx4 v[48:51], v192, s[64:65] offset:-4096
	global_load_dwordx4 v[64:67], v192, s[64:65]
	global_load_dwordx4 v[52:55], v192, s[64:65] offset:-3072
	global_load_dwordx4 v[68:71], v192, s[64:65] offset:1024
	global_load_dwordx4 v[56:59], v192, s[64:65] offset:-2048
	global_load_dwordx4 v[72:75], v192, s[64:65] offset:2048
	global_load_dwordx4 v[60:63], v192, s[64:65] offset:-1024
	global_load_dwordx4 v[76:79], v192, s[64:65] offset:3072
	v_mov_b32_e32 v216, 0
	v_mov_b32_e32 v217, 0
	v_mov_b32_e32 v218, 0
	v_mov_b32_e32 v219, 0
	v_mov_b32_e32 v80, 0
	v_mov_b32_e32 v81, 0
	v_mov_b32_e32 v82, 0
	v_mov_b32_e32 v83, 0
	v_mov_b32_e32 v84, 0
	v_mov_b32_e32 v85, 0
	v_mov_b32_e32 v86, 0
	v_mov_b32_e32 v87, 0
	v_mov_b32_e32 v88, 0
	v_mov_b32_e32 v89, 0
	v_mov_b32_e32 v90, 0
	v_mov_b32_e32 v91, 0
	v_mov_b32_e32 v92, 0
	v_mov_b32_e32 v93, 0
	v_mov_b32_e32 v94, 0
	v_mov_b32_e32 v95, 0
	v_mov_b32_e32 v96, 0
	v_mov_b32_e32 v97, 0
	v_mov_b32_e32 v98, 0
	v_mov_b32_e32 v99, 0
	v_mov_b32_e32 v100, 0
	v_mov_b32_e32 v101, 0
	v_mov_b32_e32 v102, 0
	v_mov_b32_e32 v103, 0
	v_mov_b32_e32 v104, 0
	v_mov_b32_e32 v105, 0
	v_mov_b32_e32 v106, 0
	v_mov_b32_e32 v107, 0
	v_mov_b32_e32 v108, 0
	v_mov_b32_e32 v109, 0
	v_mov_b32_e32 v110, 0
	v_mov_b32_e32 v111, 0
	v_lshlrev_b32_e32 v213, 4, v198
	ds_write_b128 v213, v[216:219] offset:0
	ds_write_b128 v213, v[216:219] offset:8192
	ds_write_b128 v213, v[216:219] offset:16384
	ds_write_b128 v213, v[216:219] offset:24576
	ds_write_b128 v213, v[216:219] offset:32768
	s_waitcnt vmcnt(20)
	ds_write_b128 v201, v[176:179]
	ds_write_b128 v201, v[180:183] offset:128
	v_add_u32_e32 v201, 17408, v201
	s_add_u32 s60, s60, 0x40000
	s_addc_u32 s61, s61, 0
	s_add_u32 s62, s62, 0x8000
	s_addc_u32 s63, s63, 0
	s_add_u32 s64, s64, 0x10000
	s_addc_u32 s65, s65, 0
	s_add_u32 s66, s66, 0x100
	s_addc_u32 s67, s67, 0
	global_load_dwordx4 v[230:233], v193, s[60:61]
	global_load_dwordx4 v[234:237], v193, s[60:61] offset:64
	global_load_dwordx4 v[238:241], v193, s[60:61] offset:128
	global_load_dwordx4 v[242:245], v193, s[60:61] offset:192
	global_load_dwordx4 v[246:249], v193, s[60:61] offset:256
	global_load_dwordx4 v[250:253], v193, s[60:61] offset:320
	global_load_dwordx4 v[184:187], v193, s[60:61] offset:384
	global_load_dwordx4 v[188:191], v193, s[60:61] offset:448
	global_load_dwordx4 v[128:131], v192, s[62:63]
	global_load_dwordx4 v[132:135], v192, s[62:63] offset:1024
	global_load_dwordx4 v[136:139], v192, s[62:63] offset:2048
	global_load_dwordx4 v[140:143], v192, s[62:63] offset:3072
	s_add_u32 s60, s60, 0x40000
	s_addc_u32 s61, s61, 0
	s_add_u32 s62, s62, 0x8000
	s_addc_u32 s63, s63, 0
	global_load_dwordx4 v[222:225], v194, s[66:67]
	global_load_dwordx4 v[226:229], v194, s[66:67] offset:128
	s_add_u32 s66, s66, 0x100
	s_addc_u32 s67, s67, 0
	s_mov_b32 s70, 0
	s_mov_b32 s80, 33792
	s_mov_b32 s81, 17408
	s_waitcnt vmcnt(0) lgkmcnt(0)
	s_barrier
